# strategy 4 other half: static s_setprio 1 for waves 0-3 in attention and scan, on top of the packed-op-split stack
# speedup vs baseline: 1.0033x; 1.0005x over previous
; DI int opaque_tid() { int t = threadIdx.x; asm volatile("" : "+v"(t)); return t; }
; DI void ph_attn(const Params& p, bf16_t* smem, int* s_item) {
;     const int tid = opaque_tid(), lane = tid & 63, w = tid >> 6, r = lane & 31, h = lane >> 5;
;     const bf16_t* PQK = (const bf16_t*)(p.ws + OFF_PQK);
;     bf16_t* MIX = (bf16_t*)(p.ws + OFF_HB);
;     const float lam = ((const float*)(p.ws + OFF_MISC))[0];
;     unsigned* ctr = (unsigned*)(p.ws + OFF_CNT);
;     const unsigned* knm = (const unsigned*)(p.ws + OFF_CNT) + 128;
;     constexpr int NQB = 33, NDIFF = NQB * 16, NITEM = NQB * 48;
;     for (;;) {
;         __syncthreads();
;         if (tid == 0) *s_item = (int)atomicAdd(ctr, 1u);
;         __syncthreads();
;         const int it = *s_item;
;         if (it >= NITEM) break;
.LBB0_592:
	s_or_b64 exec, exec, s[0:1]
	s_waitcnt lgkmcnt(0)
	v_mov_b32_e32 v0, v210
	v_mov_b32_e32 v1, 0xfa68000
	s_barrier
	v_readfirstlane_b32 s98, v210
	s_nop 3
	s_cmp_ge_u32 s98, 0x100
	s_cbranch_scc1 .Lprio_skip_3
	s_setprio 1

; DI int opaque_tid() { int t = threadIdx.x; asm volatile("" : "+v"(t)); return t; }
; DI void scan_block(const Params& p, const int u) {
;     const int tid = opaque_tid(), lane = tid & 63, r = lane & 31, h = lane >> 5;
;     const int w = __builtin_amdgcn_readfirstlane(tid >> 6);
; DI void ph_scan(const Params& p) {
;     for (int ub = blockIdx.x; ub < 256; ub += gridDim.x) {
;         const int xcd = ub & 7, j = ub >> 3;
;         scan_block(p, ((xcd * 2 + (j >> 4)) << 4) | (j & 15));
;     }
; }
.LBB0_1532:
	s_or_b64 exec, exec, s[6:7]
	s_cmpk_gt_i32 s2, 0xff
	s_waitcnt lgkmcnt(0)
	s_barrier
	s_cbranch_scc1 .LBB0_1566
	v_readfirstlane_b32 s98, v210
	s_nop 3
	s_cmp_ge_u32 s98, 0x100
	s_cbranch_scc1 .Lprio_skip_11
	s_setprio 1
